# attention 32-key half tiles (near-diagonal and far32 paths): V^T fragment LDS reads issued 4/6 ahead of their PV MFMAs, as for the 64-key tiles
# speedup vs baseline: 1.0064x; 1.0029x over previous
; DI float xor32_sum(float x) { const auto r_ = __builtin_amdgcn_permlane32_swap(__float_as_uint(x), __float_as_uint(x), false, false); return __uint_as_float(r_[0]) + __uint_as_float(r_[1]); }
; #define MFMA32(a, b, c) __builtin_amdgcn_mfma_f32_32x32x16_bf16((a), (b), (c), 0, 0, 0)
; DI bf16x8 packp(const f32x16& x, int s) { u32x4 p; p.x = pk2(x[8 * s], x[8 * s + 1]); p.y = pk2(x[8 * s + 2], x[8 * s + 3]); p.z = pk2(x[8 * s + 4], x[8 * s + 5]); p.w = pk2(x[8 * s + 6], x[8 * s + 7]); return __builtin_bit_cast(bf16x8, p); }
; DI bf16x8 lds2x4(const unsigned char* p) { const s16x4 a = *(const s16x4*)p, b = *(const s16x4*)(p + 16); return __builtin_shufflevector(a, b, 0, 1, 2, 3, 4, 5, 6, 7); }
; template <int MODE, bool FAR>
; DI void attn_tile(const unsigned char* kl  , const unsigned char* vl  ,
;                   int k0, int tq, int r, int hh, bool bit, const bf16x8 (&qf)[8], const float* lutH, f32x16 (&o)[4], float& m, float& l) {
;     ...
;     float psum = 0.f;
;     { const float msub = fmaxf(mnew, -1e29f);
; #pragma unroll
;       for (int i = 0; i < 16; ++i) { const float p = __builtin_amdgcn_exp2f(s[i] - msub); s[i] = p; psum += p; } }
;     psum = xor32_sum(psum);
;     l += psum;
;     const unsigned char* vp = vl + r * 136 + 8 * hh;
; #pragma unroll
;     for (int s2 = 0; s2 < 2; ++s2) { const bf16x8 pb = packp(s, s2);
; #pragma unroll
;         for (int dt = 0; dt < 4; ++dt) { const bf16x8 a = lds2x4(vp + dt * (32 * 136) + 32 * s2); o[dt] = MFMA32(a, pb, o[dt]); } }
.LBB0_790:
	v_max_f32_e32 v86, v86, v86
	v_max_f32_e32 v86, 0xefa18f08, v86
	v_sub_f32_e32 v4, v4, v86
	v_exp_f32_e32 v4, v4
	v_sub_f32_e32 v5, v5, v86
	v_exp_f32_e32 v5, v5
	v_sub_f32_e32 v6, v6, v86
	v_exp_f32_e32 v6, v6
	v_sub_f32_e32 v7, v7, v86
	v_exp_f32_e32 v7, v7
	v_sub_f32_e32 v8, v8, v86
	v_add_f32_e32 v87, 0, v4
	v_exp_f32_e32 v8, v8
	v_sub_f32_e32 v9, v9, v86
	v_add_f32_e32 v87, v5, v87
	v_exp_f32_e32 v9, v9
	v_sub_f32_e32 v10, v10, v86
	v_add_f32_e32 v87, v6, v87
	v_exp_f32_e32 v10, v10
	v_sub_f32_e32 v12, v12, v86
	v_add_f32_e32 v87, v7, v87
	v_exp_f32_e32 v12, v12
	v_sub_f32_e32 v13, v13, v86
	v_add_f32_e32 v87, v8, v87
	v_exp_f32_e32 v88, v13
	v_add_f32_e32 v87, v9, v87
	v_add_f32_e32 v87, v10, v87
	v_add_f32_e32 v87, v12, v87
	v_sub_f32_e32 v14, v14, v86
	v_add_f32_e32 v13, v88, v87
	v_exp_f32_e32 v87, v14
	v_sub_f32_e32 v14, v15, v86
	v_exp_f32_e32 v89, v14
	v_sub_f32_e32 v14, v82, v86
	v_exp_f32_e32 v82, v14
	v_sub_f32_e32 v14, v83, v86
	v_exp_f32_e32 v83, v14
	v_sub_f32_e32 v14, v84, v86
	v_add_f32_e32 v13, v87, v13
	v_exp_f32_e32 v84, v14
	v_sub_f32_e32 v14, v85, v86
	v_add_f32_e32 v13, v89, v13
	v_exp_f32_e32 v85, v14
	v_sub_f32_e32 v11, v11, v86
	v_add_f32_e32 v13, v82, v13
	v_exp_f32_e32 v86, v11
	v_add_f32_e32 v13, v83, v13
	v_add_f32_e32 v13, v84, v13
	v_add_f32_e32 v13, v85, v13
	v_add_f32_e32 v11, v86, v13
	v_mov_b32_e32 v13, v11
	s_nop 1
	v_permlane32_swap_b32_e32 v11, v13
	v_add_u32_e32 v90, s24, v187
	v_add_f32_e32 v11, v11, v13
	v_cvt_pk_bf16_f32 v4, v4, v5
	v_cvt_pk_bf16_f32 v5, v6, v7
	v_cvt_pk_bf16_f32 v7, v10, v12
	v_add_f32_e32 v181, v181, v11
	v_cvt_pk_bf16_f32 v6, v8, v9
	v_add_u32_e32 v240, 0x4000, v90
	v_add_u32_e32 v241, 0x5000, v90
	v_add_u32_e32 v242, 0x6000, v90
	v_add_u32_e32 v243, 0x7000, v90
	ds_read2_b64 v[224:227], v240 offset0:128 offset1:130
	ds_read2_b64 v[228:231], v241 offset0:160 offset1:162
	ds_read2_b64 v[232:235], v242 offset0:192 offset1:194
	ds_read2_b64 v[236:239], v243 offset0:224 offset1:226
	s_waitcnt lgkmcnt(3)
	v_mfma_f32_32x32x16_bf16 v[66:81], v[224:227], v[4:7], v[66:81]
	ds_read2_b64 v[224:227], v241 offset0:164 offset1:166
	s_waitcnt lgkmcnt(3)
	v_mfma_f32_32x32x16_bf16 v[50:65], v[228:231], v[4:7], v[50:65]
	ds_read2_b64 v[228:231], v242 offset0:196 offset1:198
	s_waitcnt lgkmcnt(3)
	v_mfma_f32_32x32x16_bf16 v[34:49], v[232:235], v[4:7], v[34:49]
	ds_read2_b64 v[232:235], v240 offset0:132 offset1:134
	s_waitcnt lgkmcnt(3)
	v_mfma_f32_32x32x16_bf16 v[18:33], v[236:239], v[4:7], v[18:33]
	ds_read2_b64 v[236:239], v243 offset0:228 offset1:230
	v_cvt_pk_bf16_f32 v4, v88, v87
	v_cvt_pk_bf16_f32 v5, v89, v82
	v_cvt_pk_bf16_f32 v6, v83, v84
	v_cvt_pk_bf16_f32 v7, v85, v86
	s_nop 0
	s_waitcnt lgkmcnt(3)
	v_mfma_f32_32x32x16_bf16 v[50:65], v[224:227], v[4:7], v[50:65]
	s_waitcnt lgkmcnt(2)
	v_mfma_f32_32x32x16_bf16 v[34:49], v[228:231], v[4:7], v[34:49]
	s_waitcnt lgkmcnt(1)
	v_mfma_f32_32x32x16_bf16 v[66:81], v[232:235], v[4:7], v[66:81]
	s_waitcnt lgkmcnt(0)
	v_mfma_f32_32x32x16_bf16 v[18:33], v[236:239], v[4:7], v[18:33]

; DI float xor32_sum(float x) { const auto r_ = __builtin_amdgcn_permlane32_swap(__float_as_uint(x), __float_as_uint(x), false, false); return __uint_as_float(r_[0]) + __uint_as_float(r_[1]); }
; #define MFMA32(a, b, c) __builtin_amdgcn_mfma_f32_32x32x16_bf16((a), (b), (c), 0, 0, 0)
; DI bf16x8 packp(const f32x16& x, int s) { u32x4 p; p.x = pk2(x[8 * s], x[8 * s + 1]); p.y = pk2(x[8 * s + 2], x[8 * s + 3]); p.z = pk2(x[8 * s + 4], x[8 * s + 5]); p.w = pk2(x[8 * s + 6], x[8 * s + 7]); return __builtin_bit_cast(bf16x8, p); }
; DI bf16x8 lds2x4(const unsigned char* p) { const s16x4 a = *(const s16x4*)p, b = *(const s16x4*)(p + 16); return __builtin_shufflevector(a, b, 0, 1, 2, 3, 4, 5, 6, 7); }
; template <int MODE, bool FAR>
; DI void attn_tile(const unsigned char* kl  , const unsigned char* vl  ,
;                   int k0, int tq, int r, int hh, bool bit, const bf16x8 (&qf)[8], const float* lutH, f32x16 (&o)[4], float& m, float& l) {
;     ...
;     float psum = 0.f;
;     { const float msub = fmaxf(mnew, -1e29f);
; #pragma unroll
;       for (int i = 0; i < 16; ++i) { const float p = __builtin_amdgcn_exp2f(s[i] - msub); s[i] = p; psum += p; } }
;     psum = xor32_sum(psum);
;     l += psum;
;     const unsigned char* vp = vl + r * 136 + 8 * hh;
; #pragma unroll
;     for (int s2 = 0; s2 < 2; ++s2) { const bf16x8 pb = packp(s, s2);
; #pragma unroll
;         for (int dt = 0; dt < 4; ++dt) { const bf16x8 a = lds2x4(vp + dt * (32 * 136) + 32 * s2); o[dt] = MFMA32(a, pb, o[dt]); } }
.LBB0_797:
	v_max_f32_e32 v86, v86, v86
	v_max_f32_e32 v90, 0xefa18f08, v86
	v_add_u32_e32 v98, s24, v187
	v_sub_f32_e32 v85, v85, v90
	v_sub_f32_e32 v84, v84, v90
	v_sub_f32_e32 v83, v83, v90
	v_sub_f32_e32 v82, v82, v90
	v_exp_f32_e32 v91, v85
	v_exp_f32_e32 v92, v84
	v_exp_f32_e32 v93, v83
	v_exp_f32_e32 v94, v82
	v_add_u32_e32 v240, 0x4000, v98
	v_add_u32_e32 v241, 0x5000, v98
	v_add_u32_e32 v242, 0x6000, v98
	v_add_u32_e32 v243, 0x7000, v98
	ds_read2_b64 v[224:227], v240 offset0:128 offset1:130
	ds_read2_b64 v[228:231], v241 offset0:160 offset1:162
	ds_read2_b64 v[232:235], v242 offset0:192 offset1:194
	ds_read2_b64 v[236:239], v243 offset0:224 offset1:226
	v_sub_f32_e32 v15, v15, v90
	v_sub_f32_e32 v14, v14, v90
	v_sub_f32_e32 v13, v13, v90
	v_sub_f32_e32 v12, v12, v90
	v_exp_f32_e32 v95, v15
	v_exp_f32_e32 v96, v14
	v_exp_f32_e32 v97, v13
	v_exp_f32_e32 v100, v12
	v_cvt_pk_bf16_f32 v12, v91, v92
	v_cvt_pk_bf16_f32 v13, v93, v94
	v_cvt_pk_bf16_f32 v14, v95, v96
	v_cvt_pk_bf16_f32 v15, v97, v100
	v_sub_f32_e32 v11, v11, v90
	s_waitcnt lgkmcnt(3)
	v_mfma_f32_32x32x16_bf16 v[66:81], v[224:227], v[12:15], v[66:81]
	ds_read2_b64 v[224:227], v240 offset0:132 offset1:134
	v_add_f32_e32 v82, 0, v91
	v_add_f32_e32 v91, v92, v82
	v_sub_f32_e32 v10, v10, v90
	v_sub_f32_e32 v9, v9, v90
	v_sub_f32_e32 v8, v8, v90
	v_exp_f32_e32 v92, v11
	s_waitcnt lgkmcnt(3)
	v_mfma_f32_32x32x16_bf16 v[50:65], v[228:231], v[12:15], v[50:65]
	ds_read2_b64 v[228:231], v241 offset0:164 offset1:166
	v_exp_f32_e32 v86, v10
	v_exp_f32_e32 v87, v9
	v_exp_f32_e32 v88, v8
	v_sub_f32_e32 v7, v7, v90
	v_sub_f32_e32 v6, v6, v90
	s_waitcnt lgkmcnt(3)
	v_mfma_f32_32x32x16_bf16 v[34:49], v[232:235], v[12:15], v[34:49]
	ds_read2_b64 v[232:235], v242 offset0:196 offset1:198
	v_sub_f32_e32 v5, v5, v90
	v_sub_f32_e32 v4, v4, v90
	v_exp_f32_e32 v98, v7
	v_exp_f32_e32 v103, v6
	v_exp_f32_e32 v104, v5
	v_exp_f32_e32 v90, v4
	s_waitcnt lgkmcnt(3)
	v_mfma_f32_32x32x16_bf16 v[18:33], v[236:239], v[12:15], v[18:33]
	ds_read2_b64 v[236:239], v243 offset0:228 offset1:230
	v_add_f32_e32 v12, v93, v91
	v_add_f32_e32 v12, v94, v12
	v_add_f32_e32 v12, v95, v12
	v_add_f32_e32 v12, v96, v12
	v_cvt_pk_bf16_f32 v4, v92, v86
	v_cvt_pk_bf16_f32 v5, v87, v88
	v_cvt_pk_bf16_f32 v6, v98, v103
	v_cvt_pk_bf16_f32 v7, v104, v90
	v_add_f32_e32 v12, v97, v12
	s_waitcnt lgkmcnt(3)
	v_mfma_f32_32x32x16_bf16 v[66:81], v[224:227], v[4:7], v[66:81]
	v_add_f32_e32 v82, v100, v12
	s_waitcnt lgkmcnt(2)
	v_mfma_f32_32x32x16_bf16 v[50:65], v[228:231], v[4:7], v[50:65]
	v_add_f32_e32 v8, v92, v82
	v_add_f32_e32 v8, v86, v8
	v_add_f32_e32 v8, v87, v8
	v_add_f32_e32 v8, v88, v8
	v_add_f32_e32 v8, v98, v8
	v_add_f32_e32 v82, v103, v8
	s_waitcnt lgkmcnt(1)
	v_mfma_f32_32x32x16_bf16 v[34:49], v[232:235], v[4:7], v[34:49]
	v_add_f32_e32 v12, v104, v82
	v_add_f32_e32 v12, v90, v12
	v_mov_b32_e32 v13, v12
	s_nop 1
	v_permlane32_swap_b32_e32 v12, v13
	v_add_f32_e32 v12, v12, v13
	v_add_f32_e32 v181, v181, v12
	s_waitcnt lgkmcnt(0)
	v_mfma_f32_32x32x16_bf16 v[18:33], v[236:239], v[4:7], v[18:33]

; DI float xor32_sum(float x) { const auto r_ = __builtin_amdgcn_permlane32_swap(__float_as_uint(x), __float_as_uint(x), false, false); return __uint_as_float(r_[0]) + __uint_as_float(r_[1]); }
; #define MFMA32(a, b, c) __builtin_amdgcn_mfma_f32_32x32x16_bf16((a), (b), (c), 0, 0, 0)
; DI bf16x8 packp(const f32x16& x, int s) { u32x4 p; p.x = pk2(x[8 * s], x[8 * s + 1]); p.y = pk2(x[8 * s + 2], x[8 * s + 3]); p.z = pk2(x[8 * s + 4], x[8 * s + 5]); p.w = pk2(x[8 * s + 6], x[8 * s + 7]); return __builtin_bit_cast(bf16x8, p); }
; DI bf16x8 lds2x4(const unsigned char* p) { const s16x4 a = *(const s16x4*)p, b = *(const s16x4*)(p + 16); return __builtin_shufflevector(a, b, 0, 1, 2, 3, 4, 5, 6, 7); }
; template <int MODE, bool FAR>
; DI void attn_tile(const unsigned char* kl  , const unsigned char* vl  ,
;                   int k0, int tq, int r, int hh, bool bit, const bf16x8 (&qf)[8], const float* lutH, f32x16 (&o)[4], float& m, float& l) {
;     ...
;     float psum = 0.f;
;     { const float msub = fmaxf(mnew, -1e29f);
; #pragma unroll
;       for (int i = 0; i < 16; ++i) { const float p = __builtin_amdgcn_exp2f(s[i] - msub); s[i] = p; psum += p; } }
;     psum = xor32_sum(psum);
;     l += psum;
;     const unsigned char* vp = vl + r * 136 + 8 * hh;
; #pragma unroll
;     for (int s2 = 0; s2 < 2; ++s2) { const bf16x8 pb = packp(s, s2);
; #pragma unroll
;         for (int dt = 0; dt < 4; ++dt) { const bf16x8 a = lds2x4(vp + dt * (32 * 136) + 32 * s2); o[dt] = MFMA32(a, pb, o[dt]); } }
.LBB0_816:
	v_max_f32_e32 v84, v84, v84
	v_max_f32_e32 v90, 0xefa18f08, v84
	v_sub_f32_e32 v84, v99, v90
	v_exp_f32_e32 v91, v84
	v_sub_f32_e32 v84, v98, v90
	v_add_u32_e32 v98, s20, v181
	v_sub_f32_e32 v83, v83, v90
	v_sub_f32_e32 v82, v82, v90
	v_exp_f32_e32 v92, v84
	v_exp_f32_e32 v93, v83
	v_exp_f32_e32 v94, v82
	v_add_u32_e32 v240, 0x4000, v98
	v_add_u32_e32 v241, 0x5000, v98
	v_add_u32_e32 v242, 0x6000, v98
	v_add_u32_e32 v243, 0x7000, v98
	ds_read2_b64 v[216:219], v240 offset0:128 offset1:130
	ds_read2_b64 v[220:223], v241 offset0:160 offset1:162
	ds_read2_b64 v[224:227], v242 offset0:192 offset1:194
	ds_read2_b64 v[228:231], v243 offset0:224 offset1:226
	ds_read2_b64 v[232:235], v240 offset0:132 offset1:134
	ds_read2_b64 v[236:239], v241 offset0:164 offset1:166
	v_sub_f32_e32 v15, v15, v90
	v_sub_f32_e32 v14, v14, v90
	v_sub_f32_e32 v13, v13, v90
	v_sub_f32_e32 v12, v12, v90
	v_exp_f32_e32 v95, v15
	v_exp_f32_e32 v96, v14
	v_exp_f32_e32 v97, v13
	v_exp_f32_e32 v100, v12
	v_cvt_pk_bf16_f32 v12, v91, v92
	v_cvt_pk_bf16_f32 v13, v93, v94
	v_cvt_pk_bf16_f32 v14, v95, v96
	v_cvt_pk_bf16_f32 v15, v97, v100
	s_nop 0
	s_waitcnt lgkmcnt(5)
	v_mfma_f32_32x32x16_bf16 v[66:81], v[216:219], v[12:15], v[66:81]
	ds_read2_b64 v[216:219], v242 offset0:196 offset1:198
	v_add_f32_e32 v82, 0, v91
	v_add_f32_e32 v91, v92, v82
	v_sub_f32_e32 v4, v4, v90
	v_sub_f32_e32 v7, v7, v90
	v_sub_f32_e32 v6, v6, v90
	s_waitcnt lgkmcnt(5)
	v_mfma_f32_32x32x16_bf16 v[50:65], v[220:223], v[12:15], v[50:65]
	ds_read2_b64 v[220:223], v243 offset0:228 offset1:230
	v_exp_f32_e32 v105, v7
	v_sub_f32_e32 v11, v11, v90
	v_sub_f32_e32 v10, v10, v90
	v_sub_f32_e32 v9, v9, v90
	v_sub_f32_e32 v8, v8, v90
	v_exp_f32_e32 v92, v11
	s_waitcnt lgkmcnt(5)
	v_mfma_f32_32x32x16_bf16 v[34:49], v[224:227], v[12:15], v[34:49]
	v_exp_f32_e32 v83, v4
	v_sub_f32_e32 v4, v5, v90
	v_exp_f32_e32 v82, v6
	v_exp_f32_e32 v84, v4
	v_exp_f32_e32 v103, v10
	v_exp_f32_e32 v104, v9
	v_exp_f32_e32 v85, v8
	s_waitcnt lgkmcnt(4)
	v_mfma_f32_32x32x16_bf16 v[18:33], v[228:231], v[12:15], v[18:33]
	v_cvt_pk_bf16_f32 v8, v92, v103
	v_cvt_pk_bf16_f32 v9, v104, v105
	v_cvt_pk_bf16_f32 v10, v82, v83
	v_cvt_pk_bf16_f32 v11, v84, v85
	s_nop 0
	s_waitcnt lgkmcnt(3)
	v_mfma_f32_32x32x16_bf16 v[66:81], v[232:235], v[8:11], v[66:81]
	v_add_f32_e32 v4, v93, v91
	v_add_f32_e32 v4, v94, v4
	v_add_f32_e32 v4, v95, v4
	v_add_f32_e32 v4, v96, v4
	v_add_f32_e32 v4, v97, v4
	v_add_f32_e32 v86, v100, v4
	s_waitcnt lgkmcnt(2)
	v_mfma_f32_32x32x16_bf16 v[50:65], v[236:239], v[8:11], v[50:65]
	v_add_f32_e32 v12, v92, v86
	v_add_f32_e32 v12, v103, v12
	v_add_f32_e32 v12, v104, v12
	v_add_f32_e32 v12, v105, v12
	v_add_f32_e32 v12, v82, v12
	v_add_f32_e32 v82, v83, v12
	s_waitcnt lgkmcnt(1)
	v_mfma_f32_32x32x16_bf16 v[34:49], v[216:219], v[8:11], v[34:49]
	v_add_f32_e32 v4, v84, v82
	v_add_f32_e32 v4, v85, v4
	v_mov_b32_e32 v5, v4
	s_nop 1
	v_permlane32_swap_b32_e32 v4, v5
	v_add_f32_e32 v4, v4, v5
	v_add_f32_e32 v189, v189, v4
	s_waitcnt lgkmcnt(0)
	v_mfma_f32_32x32x16_bf16 v[18:33], v[220:223], v[8:11], v[18:33]

; DI float xor32_sum(float x) { const auto r_ = __builtin_amdgcn_permlane32_swap(__float_as_uint(x), __float_as_uint(x), false, false); return __uint_as_float(r_[0]) + __uint_as_float(r_[1]); }
; #define MFMA32(a, b, c) __builtin_amdgcn_mfma_f32_32x32x16_bf16((a), (b), (c), 0, 0, 0)
; DI bf16x8 packp(const f32x16& x, int s) { u32x4 p; p.x = pk2(x[8 * s], x[8 * s + 1]); p.y = pk2(x[8 * s + 2], x[8 * s + 3]); p.z = pk2(x[8 * s + 4], x[8 * s + 5]); p.w = pk2(x[8 * s + 6], x[8 * s + 7]); return __builtin_bit_cast(bf16x8, p); }
; DI bf16x8 lds2x4(const unsigned char* p) { const s16x4 a = *(const s16x4*)p, b = *(const s16x4*)(p + 16); return __builtin_shufflevector(a, b, 0, 1, 2, 3, 4, 5, 6, 7); }
; template <int MODE, bool FAR>
; DI void attn_tile(const unsigned char* kl  , const unsigned char* vl  ,
;                   int k0, int tq, int r, int hh, bool bit, const bf16x8 (&qf)[8], const float* lutH, f32x16 (&o)[4], float& m, float& l) {
;     ...
;     float psum = 0.f;
;     { const float msub = fmaxf(mnew, -1e29f);
; #pragma unroll
;       for (int i = 0; i < 16; ++i) { const float p = __builtin_amdgcn_exp2f(s[i] - msub); s[i] = p; psum += p; } }
;     psum = xor32_sum(psum);
;     l += psum;
;     const unsigned char* vp = vl + r * 136 + 8 * hh;
; #pragma unroll
;     for (int s2 = 0; s2 < 2; ++s2) { const bf16x8 pb = packp(s, s2);
; #pragma unroll
;         for (int dt = 0; dt < 4; ++dt) { const bf16x8 a = lds2x4(vp + dt * (32 * 136) + 32 * s2); o[dt] = MFMA32(a, pb, o[dt]); } }
.LBB0_823:
	v_max_f32_e32 v86, v86, v86
	v_max_f32_e32 v94, 0xefa18f08, v86
	v_sub_f32_e32 v6, v6, v94
	v_exp_f32_e32 v95, v6
	v_sub_f32_e32 v6, v7, v94
	v_exp_f32_e32 v96, v6
	v_sub_f32_e32 v6, v8, v94
	v_exp_f32_e32 v97, v6
	v_sub_f32_e32 v6, v9, v94
	v_exp_f32_e32 v98, v6
	v_sub_f32_e32 v6, v10, v94
	v_add_u32_e32 v10, s20, v181
	v_exp_f32_e32 v99, v6
	v_sub_f32_e32 v6, v12, v94
	v_exp_f32_e32 v100, v6
	v_add_u32_e32 v240, 0x4000, v10
	v_add_u32_e32 v241, 0x5000, v10
	v_add_u32_e32 v242, 0x6000, v10
	v_add_u32_e32 v243, 0x7000, v10
	ds_read2_b64 v[216:219], v240 offset0:128 offset1:130
	ds_read2_b64 v[220:223], v241 offset0:160 offset1:162
	ds_read2_b64 v[224:227], v242 offset0:192 offset1:194
	ds_read2_b64 v[228:231], v243 offset0:224 offset1:226
	ds_read2_b64 v[232:235], v240 offset0:132 offset1:134
	ds_read2_b64 v[236:239], v241 offset0:164 offset1:166
	v_sub_f32_e32 v5, v5, v94
	v_exp_f32_e32 v5, v5
	v_sub_f32_e32 v4, v4, v94
	v_exp_f32_e32 v101, v4
	v_add_f32_e32 v4, 0, v5
	v_cvt_pk_bf16_f32 v86, v5, v95
	v_cvt_pk_bf16_f32 v87, v96, v97
	v_cvt_pk_bf16_f32 v88, v98, v99
	v_cvt_pk_bf16_f32 v89, v100, v101
	v_add_f32_e32 v95, v95, v4
	v_sub_f32_e32 v4, v84, v94
	s_waitcnt lgkmcnt(5)
	v_mfma_f32_32x32x16_bf16 v[66:81], v[216:219], v[86:89], v[66:81]
	ds_read2_b64 v[216:219], v242 offset0:196 offset1:198
	v_exp_f32_e32 v103, v4
	v_sub_f32_e32 v8, v85, v94
	s_waitcnt lgkmcnt(5)
	v_mfma_f32_32x32x16_bf16 v[50:65], v[220:223], v[86:89], v[50:65]
	ds_read2_b64 v[220:223], v243 offset0:228 offset1:230
	v_exp_f32_e32 v90, v8
	v_sub_f32_e32 v8, v82, v94
	v_exp_f32_e32 v91, v8
	v_sub_f32_e32 v8, v83, v94
	v_exp_f32_e32 v92, v8
	s_waitcnt lgkmcnt(5)
	v_mfma_f32_32x32x16_bf16 v[34:49], v[224:227], v[86:89], v[34:49]
	v_sub_f32_e32 v4, v13, v94
	v_exp_f32_e32 v105, v4
	v_sub_f32_e32 v4, v14, v94
	v_exp_f32_e32 v106, v4
	v_sub_f32_e32 v4, v15, v94
	v_exp_f32_e32 v107, v4
	v_sub_f32_e32 v8, v11, v94
	s_waitcnt lgkmcnt(4)
	v_mfma_f32_32x32x16_bf16 v[18:33], v[228:231], v[86:89], v[18:33]
	v_exp_f32_e32 v82, v8
	v_cvt_pk_bf16_f32 v8, v103, v90
	v_cvt_pk_bf16_f32 v9, v91, v92
	v_cvt_pk_bf16_f32 v10, v105, v106
	v_cvt_pk_bf16_f32 v11, v107, v82
	s_nop 0
	s_waitcnt lgkmcnt(3)
	v_mfma_f32_32x32x16_bf16 v[66:81], v[232:235], v[8:11], v[66:81]
	v_add_f32_e32 v4, v96, v95
	v_add_f32_e32 v4, v97, v4
	v_add_f32_e32 v4, v98, v4
	v_add_f32_e32 v4, v99, v4
	v_add_f32_e32 v4, v100, v4
	v_add_f32_e32 v83, v101, v4
	s_waitcnt lgkmcnt(2)
	v_mfma_f32_32x32x16_bf16 v[50:65], v[236:239], v[8:11], v[50:65]
	v_add_f32_e32 v12, v103, v83
	v_add_f32_e32 v12, v90, v12
	v_add_f32_e32 v12, v91, v12
	v_add_f32_e32 v12, v92, v12
	v_add_f32_e32 v12, v105, v12
	v_add_f32_e32 v83, v106, v12
	s_waitcnt lgkmcnt(1)
	v_mfma_f32_32x32x16_bf16 v[34:49], v[216:219], v[8:11], v[34:49]
	v_add_f32_e32 v4, v107, v83
	v_add_f32_e32 v4, v82, v4
	v_mov_b32_e32 v5, v4
	s_nop 1
	v_permlane32_swap_b32_e32 v4, v5
	v_add_f32_e32 v4, v4, v5
	v_add_f32_e32 v189, v189, v4
	s_waitcnt lgkmcnt(0)
	v_mfma_f32_32x32x16_bf16 v[18:33], v[220:223], v[8:11], v[18:33]
